# combined: PF folded norm + zero-SrcC peel + loop bookkeeping among last MFMAs (PG/PH/In/Vt) + batched loads in prologue A-prime pass, attention bias-table copy and Vt epilogue
# speedup vs baseline: 1.0095x; 1.0095x over previous
; __device__ __forceinline__ unsigned cvt_pk_bf16(float lo, float hi) { const cvt_f32x2_t v = {lo, hi}; const cvt_bf16x2_t b = __builtin_convertvector(v, cvt_bf16x2_t); return __builtin_bit_cast(unsigned, b); }
; __device__ __forceinline__ float sq4(f32x4 v) { return (v[0] * v[0] + v[1] * v[1]) + (v[2] * v[2] + v[3] * v[3]); }
; __global__ void __launch_bounds__(512, 2) fwd_kernel(Args args) {
;     ...
;                 for (int rp = front ? (pass == 0 ? (bid >= 192 ? (bid - 192) * 8 + wave : NTOK) : RA / 2 + gw) : (pass == 0 ? gw : NTOK); rp < (front && pass == 0 ? RA / 2 : NTOK / 2); rp += (front && pass == 0 ? 512 : NGW)) {
;                     const int row = 2 * rp, b = row >> 11;
;                     const f32x4* xr = (const f32x4*)(xp + (size_t)row * DM) + lane; const f32x4* gmr = (const f32x4*)(gmp + (size_t)b * DM) + lane;
;                     f32x4 v[8];
; #pragma unroll
;                     for (int j = 0; j < 8; ++j) v[j] = xr[64 * j];
;                     u32x2* o8 = (u32x2*)(axp + (size_t)row * DM) + lane; float s0 = 0.f, s1 = 0.f;
; #pragma unroll
;                     for (int j = 0; j < 8; ++j) { if (j < 4) s0 += sq4(v[j]); else s1 += sq4(v[j]); const f32x4 a = v[j] * gmr[64 * (j & 3)]; u32x2 w; w.x = cvt_pk_bf16(a[0], a[1]); w.y = cvt_pk_bf16(a[2], a[3]); o8[64 * j] = w; }
;                     s0 = wave_sum(s0); s1 = wave_sum(s1);
;                     if (lane < 32) stp[(size_t)row * 16 + lane] = lane == 0 ? s0 : (lane == 16 ? s1 : 0.f);
.LBB0_146:
	s_ashr_i32 s8, s20, 10
	s_ashr_i32 s7, s6, 31
	s_ashr_i32 s9, s8, 31
	s_lshl_b64 s[40:41], s[6:7], 12
	s_lshl_b64 s[8:9], s[8:9], 12
	v_lshl_add_u64 v[34:35], v[0:1], 0, s[40:41]
	v_lshl_add_u64 v[50:51], v[2:3], 0, s[8:9]
	s_waitcnt lgkmcnt(0)
	global_load_dwordx4 v[14:17], v[34:35], off
	global_load_dwordx4 v[54:57], v[50:51], off
	global_load_dwordx4 v[58:61], v[50:51], off offset:1024
	global_load_dwordx4 v[62:65], v[50:51], off offset:2048
	global_load_dwordx4 v[66:69], v[50:51], off offset:3072
	s_lshl_b64 s[8:9], s[6:7], 11
	v_add_co_u32_e32 v46, vcc, s72, v34
	v_lshl_add_u64 v[52:53], v[4:5], 0, s[8:9]
	s_nop 0
	v_addc_co_u32_e32 v47, vcc, 0, v35, vcc
	global_load_dwordx4 v[22:25], v[34:35], off offset:1024
	global_load_dwordx4 v[26:29], v[34:35], off offset:2048
	global_load_dwordx4 v[30:33], v[34:35], off offset:3072
	s_nop 0
	global_load_dwordx4 v[34:37], v[46:47], off
	global_load_dwordx4 v[38:41], v[46:47], off offset:1024
	global_load_dwordx4 v[42:45], v[46:47], off offset:2048
	s_nop 0
	global_load_dwordx4 v[46:49], v[46:47], off offset:3072
	s_waitcnt vmcnt(0)
	v_pk_mul_f32 v[20:21], v[16:17], v[56:57]
	v_pk_mul_f32 v[18:19], v[14:15], v[54:55]
	v_mul_f32_e32 v15, v15, v15
	v_cvt_pk_bf16_f32 v18, v18, v19
	v_cvt_pk_bf16_f32 v19, v20, v21
	global_store_dwordx2 v[52:53], v[18:19], off
	v_mul_f32_e32 v17, v17, v17
	v_fmac_f32_e32 v15, v14, v14
	v_fmac_f32_e32 v17, v16, v16
	v_add_f32_e32 v14, v15, v17
	v_pk_mul_f32 v[20:21], v[24:25], v[60:61]
	v_pk_mul_f32 v[18:19], v[22:23], v[58:59]
	v_mul_f32_e32 v23, v23, v23
	v_cvt_pk_bf16_f32 v18, v18, v19
	v_cvt_pk_bf16_f32 v19, v20, v21
	global_store_dwordx2 v[52:53], v[18:19], off offset:512
	v_mul_f32_e32 v25, v25, v25
	v_fmac_f32_e32 v23, v22, v22
	v_fmac_f32_e32 v25, v24, v24
	v_add_f32_e32 v15, v23, v25
	v_mul_f32_e32 v22, v35, v35
	v_mul_f32_e32 v23, v37, v37
	v_mul_f32_e32 v24, v39, v39
	v_mul_f32_e32 v25, v41, v41
	v_add_f32_e32 v14, v14, v15
	v_fmac_f32_e32 v22, v34, v34
	v_fmac_f32_e32 v23, v36, v36
	v_fmac_f32_e32 v24, v38, v38
	v_fmac_f32_e32 v25, v40, v40
	v_add_f32_e32 v15, v22, v23
	v_pk_mul_f32 v[20:21], v[28:29], v[64:65]
	v_pk_mul_f32 v[18:19], v[26:27], v[62:63]
	v_mul_f32_e32 v27, v27, v27
	v_cvt_pk_bf16_f32 v18, v18, v19
	v_cvt_pk_bf16_f32 v19, v20, v21
	global_store_dwordx2 v[52:53], v[18:19], off offset:1024
	v_mul_f32_e32 v29, v29, v29
	v_fmac_f32_e32 v27, v26, v26
	v_fmac_f32_e32 v29, v28, v28
	v_add_f32_e32 v16, v27, v29
	v_mul_f32_e32 v26, v43, v43
	v_mul_f32_e32 v27, v45, v45
	v_mul_f32_e32 v28, v47, v47
	v_mul_f32_e32 v29, v49, v49
	v_fmac_f32_e32 v26, v42, v42
	v_fmac_f32_e32 v27, v44, v44
	v_add_f32_e32 v14, v14, v16
	v_add_f32_e32 v16, v24, v25
	v_fmac_f32_e32 v28, v46, v46
	v_fmac_f32_e32 v29, v48, v48
	v_add_f32_e32 v22, v26, v27
	v_add_f32_e32 v15, v15, v16
	v_add_f32_e32 v23, v28, v29
	v_add_f32_e32 v15, v15, v22
	v_add_f32_e32 v15, v15, v23
	v_pk_mul_f32 v[20:21], v[32:33], v[68:69]
	v_pk_mul_f32 v[18:19], v[30:31], v[66:67]
	v_mul_f32_e32 v31, v31, v31
	v_cvt_pk_bf16_f32 v18, v18, v19
	v_cvt_pk_bf16_f32 v19, v20, v21
	global_store_dwordx2 v[52:53], v[18:19], off offset:1536
	v_mul_f32_e32 v33, v33, v33
	v_fmac_f32_e32 v31, v30, v30
	v_fmac_f32_e32 v33, v32, v32
	v_add_f32_e32 v17, v31, v33
	v_add_f32_e32 v14, v14, v17
	ds_bpermute_b32 v16, v8, v14
	ds_bpermute_b32 v17, v8, v15
	s_waitcnt lgkmcnt(1)
	v_add_f32_e32 v14, v14, v16
	s_waitcnt lgkmcnt(0)
	v_add_f32_e32 v15, v15, v17
	ds_bpermute_b32 v16, v9, v14
	ds_bpermute_b32 v17, v9, v15
	s_waitcnt lgkmcnt(1)
	v_add_f32_e32 v14, v14, v16
	s_waitcnt lgkmcnt(0)
	v_add_f32_e32 v15, v15, v17
	ds_bpermute_b32 v16, v10, v14
	ds_bpermute_b32 v17, v10, v15
	s_waitcnt lgkmcnt(1)
	v_add_f32_e32 v14, v14, v16
	s_waitcnt lgkmcnt(0)
	v_add_f32_e32 v15, v15, v17
	ds_bpermute_b32 v16, v11, v14
	ds_bpermute_b32 v17, v11, v15
	s_waitcnt lgkmcnt(1)
	v_add_f32_e32 v14, v14, v16
	s_waitcnt lgkmcnt(0)
	v_add_f32_e32 v17, v15, v17
	ds_bpermute_b32 v16, v12, v14
	ds_bpermute_b32 v22, v12, v17
	s_waitcnt lgkmcnt(1)
	v_add_f32_e32 v14, v14, v16
	s_waitcnt lgkmcnt(0)
	v_add_f32_e32 v16, v17, v22
	ds_bpermute_b32 v15, v13, v14
	ds_bpermute_b32 v17, v13, v16
	v_pk_mul_f32 v[20:21], v[36:37], v[56:57]
	v_pk_mul_f32 v[18:19], v[34:35], v[54:55]
	s_nop 0
	v_cvt_pk_bf16_f32 v18, v18, v19
	v_cvt_pk_bf16_f32 v19, v20, v21
	global_store_dwordx2 v[52:53], v[18:19], off offset:2048
	v_pk_mul_f32 v[20:21], v[40:41], v[60:61]
	v_pk_mul_f32 v[18:19], v[38:39], v[58:59]
	s_nop 0
	v_cvt_pk_bf16_f32 v18, v18, v19
	v_cvt_pk_bf16_f32 v19, v20, v21
	global_store_dwordx2 v[52:53], v[18:19], off offset:2560
	v_pk_mul_f32 v[20:21], v[44:45], v[64:65]
	v_pk_mul_f32 v[18:19], v[42:43], v[62:63]
	s_nop 0
	v_cvt_pk_bf16_f32 v18, v18, v19
	v_cvt_pk_bf16_f32 v19, v20, v21
	global_store_dwordx2 v[52:53], v[18:19], off offset:3072
	v_pk_mul_f32 v[20:21], v[48:49], v[68:69]
	v_pk_mul_f32 v[18:19], v[46:47], v[66:67]
	s_nop 0
	v_cvt_pk_bf16_f32 v18, v18, v19
	v_cvt_pk_bf16_f32 v19, v20, v21
	global_store_dwordx2 v[52:53], v[18:19], off offset:3584
	s_and_saveexec_b64 s[8:9], s[42:43]
	s_cbranch_execz .LBB0_145
	s_waitcnt lgkmcnt(1)
	v_add_f32_e32 v14, v14, v15
	s_waitcnt lgkmcnt(0)
	v_add_f32_e32 v15, v16, v17
	s_lshl_b64 s[40:41], s[6:7], 6
	v_cndmask_b32_e64 v15, 0, v15, s[46:47]
	v_lshl_add_u64 v[18:19], v[6:7], 0, s[40:41]
	v_cndmask_b32_e64 v14, v15, v14, s[44:45]
	global_store_dword v[18:19], v14, off
	s_branch .LBB0_145

; #define LAS __attribute__((address_space(3)))
; __device__ __forceinline__ unsigned cvt_pk_bf16(float lo, float hi) { const cvt_f32x2_t v = {lo, hi}; const cvt_bf16x2_t b = __builtin_convertvector(v, cvt_bf16x2_t); return __builtin_bit_cast(unsigned, b); }
;     __device__ __forceinline__ void operator()(const f32x4 (&acc)[2][2][4][2], const Unit& u, int wr, int wc, int fr, int fq) const {
;         const int b = u.pn >> 3, t0 = (u.pn & 7) * 256 + wc * 32 + 8 * fq;
;         tile_rstd_to_lds(statx, u.pn * 256, rsl, wr, wc, fr, fq);
;         float rs[2][8];
; #pragma unroll
;         for (int bj = 0; bj < 2; ++bj) { const f32x4 r0_ = *(const LAS f32x4*)(rsl + 128 * bj + wc * 32 + 8 * fq), r1_ = *(const LAS f32x4*)(rsl + 128 * bj + wc * 32 + 8 * fq + 4);
;             rs[bj][0] = r0_[0]; rs[bj][1] = r0_[1]; rs[bj][2] = r0_[2]; rs[bj][3] = r0_[3]; rs[bj][4] = r1_[0]; rs[bj][5] = r1_[1]; rs[bj][6] = r1_[2]; rs[bj][7] = r1_[3]; }
; #pragma unroll
;         for (int ai = 0; ai < 2; ++ai)
; #pragma unroll
;             for (int m = 0; m < 4; ++m) {
;                 const int cv = u.pm * 256 + ai * 128 + wr * 64 + m * 16 + fr;
;                 const float sh = shw[(size_t)b * INC + 1024 + cv];
;                 const int head = u.pm * 4 + ai * 2 + wr;
; #pragma unroll
;                 for (int bj = 0; bj < 2; ++bj) {
;                     const int rrow = (u.pn & 7) * 4 + bj * 2 + (wc >> 1), kb = wc & 1;
;                     bf16_t* dst = VT + (((((size_t)(b * 32 + rrow) * 8 + head) * 2 + kb) * 4 + m) * 512) + (size_t)(fq * 16 + fr) * 8;
;                     const f32x4 a = acc[ai][bj][m][0], c = acc[ai][bj][m][1];
;                     u32x4 w; w.x = cvt_pk_bf16(a[0] * rs[bj][0] + sh, a[1] * rs[bj][1] + sh); w.y = cvt_pk_bf16(a[2] * rs[bj][2] + sh, a[3] * rs[bj][3] + sh);
;                     w.z = cvt_pk_bf16(c[0] * rs[bj][4] + sh, c[1] * rs[bj][5] + sh); w.w = cvt_pk_bf16(c[2] * rs[bj][6] + sh, c[3] * rs[bj][7] + sh);
;                     *(u32x4*)dst = w;
;                 }
.LBB0_576:
	s_or_b64 exec, exec, s[44:45]
	s_lshl_b32 s4, s85, 8
	s_add_i32 s4, s4, s64
	v_add_u32_e32 v154, s4, v154
	s_lshl_b32 s4, s85, 2
	s_add_i32 s46, s4, s52
	s_lshl_b32 s4, s84, 2
	s_ashr_i32 s44, s84, 3
	s_and_b32 s4, s4, 28
	s_ashr_i32 s45, s44, 31
	s_or_b32 s4, s76, s4
	s_lshl_b32 s5, s44, 5
	s_lshl_b64 s[48:49], s[44:45], 13
	s_or_b32 s84, s4, s5
	s_ashr_i32 s47, s46, 31
	s_add_u32 s4, s58, s48
	s_addc_u32 s5, s59, s49
	s_add_u32 s44, s4, 0x401000
	v_ashrrev_i32_e32 v155, 31, v154
	s_addc_u32 s45, s5, 0
	s_waitcnt lgkmcnt(0)
	s_barrier
	v_lshl_add_u32 v64, v64, 5, s80
	v_lshl_add_u64 v[158:159], v[154:155], 2, s[44:45]
	ds_read_b128 v[76:79], v64
	ds_read_b128 v[72:75], v64 offset:16
	ds_read_b128 v[68:71], v64 offset:512
	ds_read_b128 v[64:67], v64 offset:528
	global_load_dword v164, v[158:159], off
	global_load_dword v229, v[158:159], off offset:64
	global_load_dword v230, v[158:159], off offset:128
	global_load_dword v231, v[158:159], off offset:192
	global_load_dword v232, v[158:159], off offset:512
	global_load_dword v233, v[158:159], off offset:576
	global_load_dword v234, v[158:159], off offset:640
	global_load_dword v235, v[158:159], off offset:704
	s_ashr_i32 s85, s84, 31
	s_lshl_b64 s[48:49], s[84:85], 16
	s_lshl_b64 s[86:87], s[46:47], 13
	s_add_u32 s17, s62, s48
	s_addc_u32 s21, s63, s49
	s_add_u32 s4, s17, s86
	s_addc_u32 s5, s21, s87
	v_ashrrev_i32_e32 v157, 31, v156
	s_add_u32 s48, s4, s77
	v_lshlrev_b64 v[156:157], 4, v[156:157]
	s_addc_u32 s49, s5, 0
	v_lshl_add_u64 v[158:159], s[48:49], 0, v[156:157]
	s_or_b32 s48, s84, 2
	s_ashr_i32 s49, s48, 31
	s_lshl_b64 s[48:49], s[48:49], 16
	s_add_u32 s47, s62, s48
	s_addc_u32 s48, s63, s49
	s_add_u32 s4, s47, s86
	s_addc_u32 s5, s48, s87
	s_add_u32 s84, s4, s77
	s_addc_u32 s85, s5, 0
	s_waitcnt vmcnt(0) lgkmcnt(0)
	v_pk_fma_f32 v[132:133], v[132:133], v[68:69], v[164:165] op_sel_hi:[1,1,0]
	v_pk_fma_f32 v[134:135], v[134:135], v[70:71], v[164:165] op_sel_hi:[1,1,0]
	v_pk_fma_f32 v[128:129], v[128:129], v[64:65], v[164:165] op_sel_hi:[1,1,0]
	v_pk_fma_f32 v[140:141], v[140:141], v[76:77], v[164:165] op_sel_hi:[1,1,0]
	v_pk_fma_f32 v[142:143], v[142:143], v[78:79], v[164:165] op_sel_hi:[1,1,0]
	v_pk_fma_f32 v[136:137], v[136:137], v[72:73], v[164:165] op_sel_hi:[1,1,0]
	v_cvt_pk_bf16_f32 v132, v132, v133
	v_cvt_pk_bf16_f32 v133, v134, v135
	v_cvt_pk_bf16_f32 v134, v128, v129
	v_pk_fma_f32 v[128:129], v[130:131], v[66:67], v[164:165] op_sel_hi:[1,1,0]
	v_cvt_pk_bf16_f32 v140, v140, v141
	v_cvt_pk_bf16_f32 v141, v142, v143
	v_cvt_pk_bf16_f32 v142, v136, v137
	v_pk_fma_f32 v[136:137], v[138:139], v[74:75], v[164:165] op_sel_hi:[1,1,0]
	v_cvt_pk_bf16_f32 v135, v128, v129
	v_add_u32_e32 v128, 16, v154
	v_cvt_pk_bf16_f32 v143, v136, v137
	v_lshl_add_u64 v[136:137], s[84:85], 0, v[156:157]
	v_ashrrev_i32_e32 v129, 31, v128
	global_store_dwordx4 v[158:159], v[140:143], off
	global_store_dwordx4 v[136:137], v[132:135], off
	v_lshl_add_u64 v[128:129], v[128:129], 2, s[44:45]
	v_mov_b32_e32 v128, v229
	s_add_i32 s84, s46, 2
	s_ashr_i32 s85, s84, 31
	s_lshl_b64 s[84:85], s[84:85], 13
	s_add_u32 s4, s17, s84
	s_addc_u32 s5, s21, s85
	s_add_u32 s86, s4, s77
	s_addc_u32 s87, s5, 0
	s_add_u32 s4, s47, s84
	s_addc_u32 s5, s48, s85
	s_add_u32 s46, s4, s77
	s_addc_u32 s47, s5, 0
	s_andn2_b64 vcc, exec, s[42:43]
	v_pk_fma_f32 v[116:117], v[116:117], v[68:69], v[128:129] op_sel_hi:[1,1,0]
	v_pk_fma_f32 v[118:119], v[118:119], v[70:71], v[128:129] op_sel_hi:[1,1,0]
	v_pk_fma_f32 v[112:113], v[112:113], v[64:65], v[128:129] op_sel_hi:[1,1,0]
	v_pk_fma_f32 v[124:125], v[124:125], v[76:77], v[128:129] op_sel_hi:[1,1,0]
	v_pk_fma_f32 v[126:127], v[126:127], v[78:79], v[128:129] op_sel_hi:[1,1,0]
	v_pk_fma_f32 v[120:121], v[120:121], v[72:73], v[128:129] op_sel_hi:[1,1,0]
	v_cvt_pk_bf16_f32 v116, v116, v117
	v_cvt_pk_bf16_f32 v117, v118, v119
	v_cvt_pk_bf16_f32 v118, v112, v113
	v_pk_fma_f32 v[112:113], v[114:115], v[66:67], v[128:129] op_sel_hi:[1,1,0]
	v_cvt_pk_bf16_f32 v124, v124, v125
	v_cvt_pk_bf16_f32 v125, v126, v127
	v_cvt_pk_bf16_f32 v126, v120, v121
	v_pk_fma_f32 v[120:121], v[122:123], v[74:75], v[128:129] op_sel_hi:[1,1,0]
	v_cvt_pk_bf16_f32 v119, v112, v113
	v_add_u32_e32 v112, 32, v154
	v_cvt_pk_bf16_f32 v127, v120, v121
	v_ashrrev_i32_e32 v113, 31, v112
	global_store_dwordx4 v[158:159], v[124:127], off offset:1024
	global_store_dwordx4 v[136:137], v[116:119], off offset:1024
	v_lshl_add_u64 v[112:113], v[112:113], 2, s[44:45]
	v_mov_b32_e32 v112, v230
	v_pk_fma_f32 v[100:101], v[100:101], v[68:69], v[112:113] op_sel_hi:[1,1,0]
	v_pk_fma_f32 v[102:103], v[102:103], v[70:71], v[112:113] op_sel_hi:[1,1,0]
	v_pk_fma_f32 v[96:97], v[96:97], v[64:65], v[112:113] op_sel_hi:[1,1,0]
	v_pk_fma_f32 v[108:109], v[108:109], v[76:77], v[112:113] op_sel_hi:[1,1,0]
	v_pk_fma_f32 v[110:111], v[110:111], v[78:79], v[112:113] op_sel_hi:[1,1,0]
	v_pk_fma_f32 v[104:105], v[104:105], v[72:73], v[112:113] op_sel_hi:[1,1,0]
	v_cvt_pk_bf16_f32 v100, v100, v101
	v_cvt_pk_bf16_f32 v101, v102, v103
	v_cvt_pk_bf16_f32 v102, v96, v97
	v_pk_fma_f32 v[96:97], v[98:99], v[66:67], v[112:113] op_sel_hi:[1,1,0]
	v_cvt_pk_bf16_f32 v108, v108, v109
	v_cvt_pk_bf16_f32 v109, v110, v111
	v_cvt_pk_bf16_f32 v110, v104, v105
	v_pk_fma_f32 v[104:105], v[106:107], v[74:75], v[112:113] op_sel_hi:[1,1,0]
	v_cvt_pk_bf16_f32 v103, v96, v97
	v_add_u32_e32 v96, 48, v154
	v_cvt_pk_bf16_f32 v111, v104, v105
	v_ashrrev_i32_e32 v97, 31, v96
	global_store_dwordx4 v[158:159], v[108:111], off offset:2048
	global_store_dwordx4 v[136:137], v[100:103], off offset:2048
; __device__ __forceinline__ unsigned cvt_pk_bf16(float lo, float hi) { const cvt_f32x2_t v = {lo, hi}; const cvt_bf16x2_t b = __builtin_convertvector(v, cvt_bf16x2_t); return __builtin_bit_cast(unsigned, b); }
;     __device__ __forceinline__ void operator()(const f32x4 (&acc)[2][2][4][2], const Unit& u, int wr, int wc, int fr, int fq) const {
;     ...
; #pragma unroll
;         for (int ai = 0; ai < 2; ++ai)
; #pragma unroll
;             for (int m = 0; m < 4; ++m) {
;                 const int cv = u.pm * 256 + ai * 128 + wr * 64 + m * 16 + fr;
;                 const float sh = shw[(size_t)b * INC + 1024 + cv];
;                 const int head = u.pm * 4 + ai * 2 + wr;
; #pragma unroll
;                 for (int bj = 0; bj < 2; ++bj) {
;                     const int rrow = (u.pn & 7) * 4 + bj * 2 + (wc >> 1), kb = wc & 1;
;                     bf16_t* dst = VT + (((((size_t)(b * 32 + rrow) * 8 + head) * 2 + kb) * 4 + m) * 512) + (size_t)(fq * 16 + fr) * 8;
;                     const f32x4 a = acc[ai][bj][m][0], c = acc[ai][bj][m][1];
;                     u32x4 w; w.x = cvt_pk_bf16(a[0] * rs[bj][0] + sh, a[1] * rs[bj][1] + sh); w.y = cvt_pk_bf16(a[2] * rs[bj][2] + sh, a[3] * rs[bj][3] + sh);
;                     w.z = cvt_pk_bf16(c[0] * rs[bj][4] + sh, c[1] * rs[bj][5] + sh); w.w = cvt_pk_bf16(c[2] * rs[bj][6] + sh, c[3] * rs[bj][7] + sh);
;                     *(u32x4*)dst = w;
;                 }
	v_lshl_add_u64 v[96:97], v[96:97], 2, s[44:45]
	v_mov_b32_e32 v96, v231
	v_pk_fma_f32 v[84:85], v[84:85], v[68:69], v[96:97] op_sel_hi:[1,1,0]
	v_pk_fma_f32 v[86:87], v[86:87], v[70:71], v[96:97] op_sel_hi:[1,1,0]
	v_pk_fma_f32 v[80:81], v[80:81], v[64:65], v[96:97] op_sel_hi:[1,1,0]
	v_pk_fma_f32 v[92:93], v[92:93], v[76:77], v[96:97] op_sel_hi:[1,1,0]
	v_pk_fma_f32 v[94:95], v[94:95], v[78:79], v[96:97] op_sel_hi:[1,1,0]
	v_pk_fma_f32 v[88:89], v[88:89], v[72:73], v[96:97] op_sel_hi:[1,1,0]
	v_cvt_pk_bf16_f32 v84, v84, v85
	v_cvt_pk_bf16_f32 v85, v86, v87
	v_cvt_pk_bf16_f32 v86, v80, v81
	v_pk_fma_f32 v[80:81], v[82:83], v[66:67], v[96:97] op_sel_hi:[1,1,0]
	v_cvt_pk_bf16_f32 v92, v92, v93
	v_cvt_pk_bf16_f32 v93, v94, v95
	v_cvt_pk_bf16_f32 v94, v88, v89
	v_pk_fma_f32 v[88:89], v[90:91], v[74:75], v[96:97] op_sel_hi:[1,1,0]
	v_cvt_pk_bf16_f32 v87, v80, v81
	v_add_u32_e32 v80, 0x80, v154
	v_cvt_pk_bf16_f32 v95, v88, v89
	v_ashrrev_i32_e32 v81, 31, v80
	global_store_dwordx4 v[158:159], v[92:95], off offset:3072
	global_store_dwordx4 v[136:137], v[84:87], off offset:3072
	v_lshl_add_u64 v[80:81], v[80:81], 2, s[44:45]
	v_mov_b32_e32 v82, v232
	v_lshl_add_u64 v[80:81], s[86:87], 0, v[156:157]
	v_pk_fma_f32 v[52:53], v[52:53], v[68:69], v[82:83] op_sel_hi:[1,1,0]
	v_pk_fma_f32 v[54:55], v[54:55], v[70:71], v[82:83] op_sel_hi:[1,1,0]
	v_pk_fma_f32 v[48:49], v[48:49], v[64:65], v[82:83] op_sel_hi:[1,1,0]
	v_pk_fma_f32 v[60:61], v[60:61], v[76:77], v[82:83] op_sel_hi:[1,1,0]
	v_pk_fma_f32 v[62:63], v[62:63], v[78:79], v[82:83] op_sel_hi:[1,1,0]
	v_pk_fma_f32 v[56:57], v[56:57], v[72:73], v[82:83] op_sel_hi:[1,1,0]
	v_cvt_pk_bf16_f32 v52, v52, v53
	v_cvt_pk_bf16_f32 v53, v54, v55
	v_cvt_pk_bf16_f32 v54, v48, v49
	v_pk_fma_f32 v[48:49], v[50:51], v[66:67], v[82:83] op_sel_hi:[1,1,0]
	v_cvt_pk_bf16_f32 v60, v60, v61
	v_cvt_pk_bf16_f32 v61, v62, v63
	v_cvt_pk_bf16_f32 v62, v56, v57
	v_pk_fma_f32 v[56:57], v[58:59], v[74:75], v[82:83] op_sel_hi:[1,1,0]
	v_cvt_pk_bf16_f32 v55, v48, v49
	v_add_u32_e32 v48, 0x90, v154
	v_cvt_pk_bf16_f32 v63, v56, v57
	v_lshl_add_u64 v[56:57], s[46:47], 0, v[156:157]
	v_ashrrev_i32_e32 v49, 31, v48
	global_store_dwordx4 v[80:81], v[60:63], off
	global_store_dwordx4 v[56:57], v[52:55], off
	v_lshl_add_u64 v[48:49], v[48:49], 2, s[44:45]
	v_mov_b32_e32 v48, v233
	v_pk_fma_f32 v[36:37], v[36:37], v[68:69], v[48:49] op_sel_hi:[1,1,0]
	v_pk_fma_f32 v[38:39], v[38:39], v[70:71], v[48:49] op_sel_hi:[1,1,0]
	v_pk_fma_f32 v[32:33], v[32:33], v[64:65], v[48:49] op_sel_hi:[1,1,0]
	v_pk_fma_f32 v[44:45], v[44:45], v[76:77], v[48:49] op_sel_hi:[1,1,0]
	v_pk_fma_f32 v[46:47], v[46:47], v[78:79], v[48:49] op_sel_hi:[1,1,0]
	v_pk_fma_f32 v[40:41], v[40:41], v[72:73], v[48:49] op_sel_hi:[1,1,0]
	v_cvt_pk_bf16_f32 v36, v36, v37
	v_cvt_pk_bf16_f32 v37, v38, v39
	v_cvt_pk_bf16_f32 v38, v32, v33
	v_pk_fma_f32 v[32:33], v[34:35], v[66:67], v[48:49] op_sel_hi:[1,1,0]
	v_cvt_pk_bf16_f32 v44, v44, v45
	v_cvt_pk_bf16_f32 v45, v46, v47
	v_cvt_pk_bf16_f32 v46, v40, v41
	v_pk_fma_f32 v[40:41], v[42:43], v[74:75], v[48:49] op_sel_hi:[1,1,0]
	v_cvt_pk_bf16_f32 v39, v32, v33
	v_add_u32_e32 v32, 0xa0, v154
	v_cvt_pk_bf16_f32 v47, v40, v41
	v_ashrrev_i32_e32 v33, 31, v32
	global_store_dwordx4 v[80:81], v[44:47], off offset:1024
	global_store_dwordx4 v[56:57], v[36:39], off offset:1024
	v_lshl_add_u64 v[32:33], v[32:33], 2, s[44:45]
	v_mov_b32_e32 v32, v234
	v_pk_fma_f32 v[20:21], v[20:21], v[68:69], v[32:33] op_sel_hi:[1,1,0]
	v_pk_fma_f32 v[22:23], v[22:23], v[70:71], v[32:33] op_sel_hi:[1,1,0]
	v_pk_fma_f32 v[16:17], v[16:17], v[64:65], v[32:33] op_sel_hi:[1,1,0]
	v_pk_fma_f32 v[28:29], v[28:29], v[76:77], v[32:33] op_sel_hi:[1,1,0]
	v_pk_fma_f32 v[30:31], v[30:31], v[78:79], v[32:33] op_sel_hi:[1,1,0]
	v_pk_fma_f32 v[24:25], v[24:25], v[72:73], v[32:33] op_sel_hi:[1,1,0]
	v_cvt_pk_bf16_f32 v20, v20, v21
	v_cvt_pk_bf16_f32 v21, v22, v23
	v_cvt_pk_bf16_f32 v22, v16, v17
	v_pk_fma_f32 v[16:17], v[18:19], v[66:67], v[32:33] op_sel_hi:[1,1,0]
	v_cvt_pk_bf16_f32 v28, v28, v29
	v_cvt_pk_bf16_f32 v29, v30, v31
	v_cvt_pk_bf16_f32 v30, v24, v25
	v_pk_fma_f32 v[24:25], v[26:27], v[74:75], v[32:33] op_sel_hi:[1,1,0]
	v_cvt_pk_bf16_f32 v23, v16, v17
	v_add_u32_e32 v16, 0xb0, v154
	v_cvt_pk_bf16_f32 v31, v24, v25
	v_ashrrev_i32_e32 v17, 31, v16
	global_store_dwordx4 v[80:81], v[28:31], off offset:2048
	global_store_dwordx4 v[56:57], v[20:23], off offset:2048
	v_lshl_add_u64 v[16:17], v[16:17], 2, s[44:45]
	v_mov_b32_e32 v16, v235
	s_mov_b64 s[44:45], -1
	v_pk_fma_f32 v[12:13], v[12:13], v[76:77], v[16:17] op_sel_hi:[1,1,0]
	v_pk_fma_f32 v[14:15], v[14:15], v[78:79], v[16:17] op_sel_hi:[1,1,0]
	v_pk_fma_f32 v[8:9], v[8:9], v[72:73], v[16:17] op_sel_hi:[1,1,0]
	v_pk_fma_f32 v[4:5], v[4:5], v[68:69], v[16:17] op_sel_hi:[1,1,0]
	v_pk_fma_f32 v[6:7], v[6:7], v[70:71], v[16:17] op_sel_hi:[1,1,0]
	v_pk_fma_f32 v[0:1], v[0:1], v[64:65], v[16:17] op_sel_hi:[1,1,0]
	v_cvt_pk_bf16_f32 v12, v12, v13
	v_cvt_pk_bf16_f32 v13, v14, v15
	v_cvt_pk_bf16_f32 v14, v8, v9
	v_pk_fma_f32 v[8:9], v[10:11], v[74:75], v[16:17] op_sel_hi:[1,1,0]
	v_cvt_pk_bf16_f32 v4, v4, v5
	v_cvt_pk_bf16_f32 v5, v6, v7
	v_cvt_pk_bf16_f32 v6, v0, v1
	v_pk_fma_f32 v[0:1], v[2:3], v[66:67], v[16:17] op_sel_hi:[1,1,0]
	v_cvt_pk_bf16_f32 v15, v8, v9
	v_cvt_pk_bf16_f32 v7, v0, v1
	global_store_dwordx4 v[80:81], v[12:15], off offset:3072
	global_store_dwordx4 v[56:57], v[4:7], off offset:3072
	s_cbranch_vccnz .LBB0_563
	v_readlane_b32 s4, v255, 36
	v_readlane_b32 s5, v255, 37
	s_andn2_b64 vcc, exec, s[4:5]
	s_cbranch_vccnz .LBB0_562
	s_barrier
	s_branch .LBB0_562

; #define LAS __attribute__((address_space(3)))
; __device__ __forceinline__ void attn_phase(LAS unsigned char* lds, const bf16_t* Qb, const bf16_t* Kb, const bf16_t* VT, bf16_t* MIX,
;                                            const float* tblg, const float* ga) {
;     int tid = threadIdx.x; asm volatile("" : "+v"(tid));
;     const int h = __builtin_amdgcn_readfirstlane(tid >> 6), lane = tid & 63, fr = lane & 15, fq = lane >> 4;
;     LAS float* tbl = (LAS float*)lds;
;     LAS float* red = (LAS float*)(lds + 61440);
; #pragma unroll
;     for (int i4 = 0; i4 < 8; ++i4) { const int i = tid + 512 * i4; if (i < NH * 15 * 128 / 4) ((LAS f32x4*)tbl)[i] = ((const f32x4*)tblg)[i]; }
.LBB0_627:
	s_mov_b64 s[4:5], s[0:1]
	s_mov_b64 s[6:7], s[0:1]
	s_load_dwordx2 s[4:5], s[4:5], 0xc8
	s_mov_b64 s[8:9], s[0:1]
	s_load_dwordx2 s[6:7], s[6:7], 0xc8
	s_mov_b64 s[16:17], s[0:1]
	s_load_dwordx2 s[8:9], s[8:9], 0xc8
	s_waitcnt lgkmcnt(0)
	s_mov_b64 s[20:21], s[0:1]
	s_load_dwordx2 s[16:17], s[16:17], 0xc8
	s_load_dwordx2 s[20:21], s[20:21], 0xc8
	v_readlane_b32 s22, v255, 32
	v_readlane_b32 s23, v255, 33
	s_mov_b32 s38, s22
	s_mul_i32 s23, s38, 0xf000
	s_mul_hi_i32 s22, s22, 0xf000
	s_waitcnt lgkmcnt(0)
	s_add_u32 s20, s20, s23
	s_addc_u32 s21, s21, s22
	s_add_u32 s22, s20, 0x380000
	s_addc_u32 s23, s21, 0
	s_mov_b64 s[20:21], s[0:1]
	s_load_dwordx2 s[20:21], s[20:21], 0x98
	v_mov_b32_e32 v0, v209
	s_movk_i32 s38, 0xf00
	s_movk_i32 s44, 0x300
	s_nop 0
	v_readfirstlane_b32 s40, v0
	v_cmp_gt_i32_e32 vcc, s38, v0
	v_ashrrev_i32_e32 v1, 31, v0
	v_lshl_add_u32 v2, v0, 4, 0
	s_and_saveexec_b64 s[38:39], vcc
	s_cbranch_execz .LBB0_629
	v_lshl_add_u64 v[4:5], v[0:1], 4, s[22:23]
	global_load_dwordx4 v[8:11], v[4:5], off
.LBB0_629:
	s_or_b64 exec, exec, s[38:39]
	s_movk_i32 s38, 0xd00
	v_cmp_gt_i32_e32 vcc, s38, v0
	s_and_saveexec_b64 s[38:39], vcc
	s_cbranch_execz .LBB0_631
	v_lshl_add_u64 v[4:5], v[0:1], 4, s[22:23]
	v_add_co_u32_e32 v4, vcc, 0x2000, v4
	s_nop 1
	v_addc_co_u32_e32 v5, vcc, 0, v5, vcc
	global_load_dwordx4 v[12:15], v[4:5], off
.LBB0_631:
	s_or_b64 exec, exec, s[38:39]
	s_movk_i32 s38, 0xb00
	v_cmp_gt_i32_e32 vcc, s38, v0
	s_and_saveexec_b64 s[38:39], vcc
	s_cbranch_execz .LBB0_633
	v_lshl_add_u64 v[4:5], v[0:1], 4, s[22:23]
	v_add_co_u32_e32 v4, vcc, 0x4000, v4
	s_nop 1
	v_addc_co_u32_e32 v5, vcc, 0, v5, vcc
	global_load_dwordx4 v[16:19], v[4:5], off
.LBB0_633:
	s_or_b64 exec, exec, s[38:39]
	s_movk_i32 s38, 0x900
	v_cmp_gt_i32_e32 vcc, s38, v0
	s_and_saveexec_b64 s[38:39], vcc
	s_cbranch_execz .LBB0_635
	v_lshl_add_u64 v[4:5], v[0:1], 4, s[22:23]
	v_add_co_u32_e32 v4, vcc, 0x6000, v4
	s_nop 1
	v_addc_co_u32_e32 v5, vcc, 0, v5, vcc
	global_load_dwordx4 v[20:23], v[4:5], off
.LBB0_635:
	s_or_b64 exec, exec, s[38:39]
	s_movk_i32 s38, 0x700
	v_cmp_gt_i32_e32 vcc, s38, v0
	s_and_saveexec_b64 s[38:39], vcc
	s_cbranch_execz .LBB0_637
	v_lshl_add_u64 v[4:5], v[0:1], 4, s[22:23]
	v_add_co_u32_e32 v4, vcc, 0x8000, v4
	s_nop 1
	v_addc_co_u32_e32 v5, vcc, 0, v5, vcc
	global_load_dwordx4 v[24:27], v[4:5], off
.LBB0_637:
	s_or_b64 exec, exec, s[38:39]
	s_movk_i32 s38, 0x500
	v_cmp_gt_i32_e32 vcc, s38, v0
	s_and_saveexec_b64 s[38:39], vcc
	s_cbranch_execz .LBB0_639
	v_lshl_add_u64 v[4:5], v[0:1], 4, s[22:23]
	v_add_co_u32_e32 v4, vcc, 0xa000, v4
	s_nop 1
	v_addc_co_u32_e32 v5, vcc, 0, v5, vcc
	global_load_dwordx4 v[28:31], v[4:5], off
.LBB0_639:
	s_or_b64 exec, exec, s[38:39]
	v_cmp_gt_i32_e32 vcc, s44, v0
	s_and_saveexec_b64 s[38:39], vcc
	s_cbranch_execz .LBB0_641
	v_lshl_add_u64 v[4:5], v[0:1], 4, s[22:23]
	v_add_co_u32_e32 v4, vcc, 0xc000, v4
	s_nop 1
	v_addc_co_u32_e32 v5, vcc, 0, v5, vcc
	global_load_dwordx4 v[32:35], v[4:5], off
.LBB0_641:
	s_or_b64 exec, exec, s[38:39]
	s_movk_i32 s38, 0x100
	v_cmp_gt_i32_e32 vcc, s38, v0
	s_and_saveexec_b64 s[38:39], vcc
	s_cbranch_execz .LBB0_643
	v_lshl_add_u64 v[4:5], v[0:1], 4, s[22:23]
	v_add_co_u32_e32 v4, vcc, 0xe000, v4
	s_nop 1
	v_addc_co_u32_e32 v5, vcc, 0, v5, vcc
	global_load_dwordx4 v[36:39], v[4:5], off
; #define LAS __attribute__((address_space(3)))
; __device__ __forceinline__ void attn_phase(LAS unsigned char* lds, const bf16_t* Qb, const bf16_t* Kb, const bf16_t* VT, bf16_t* MIX,
;                                            const float* tblg, const float* ga) {
;     ...
;     for (int i4 = 0; i4 < 8; ++i4) { const int i = tid + 512 * i4; if (i < NH * 15 * 128 / 4) ((LAS f32x4*)tbl)[i] = ((const f32x4*)tblg)[i]; }
;     __syncthreads();
;     LAS u32x4* mskl = (LAS u32x4*)(lds + 63488);
;     if (h == 0) {
; #pragma unroll
;         for (int qt = 0; qt < 4; ++qt)
; #pragma unroll
;             for (int kb = 0; kb < 2; ++kb) {
;                 if ((qt == 0 && kb == 1) || (qt == 3 && kb == 0)) continue;
;                 const int bi = qt == 0 ? 0 : (qt == 1 ? 1 + kb : (qt == 2 ? 3 + kb : 5));
;                 const int qc = 16 * qt + fr, cs = min(max(qc - 8, 0), 48), d = 32 * kb + 8 * fq - cs;
;                 u32x4 mm;
;                 mm.x = (((unsigned)(d + 0) < 16u) ? 0xffffu : 0u) | (((unsigned)(d + 1) < 16u) ? 0xffff0000u : 0u);
;                 mm.y = (((unsigned)(d + 2) < 16u) ? 0xffffu : 0u) | (((unsigned)(d + 3) < 16u) ? 0xffff0000u : 0u);
;                 mm.z = (((unsigned)(d + 4) < 16u) ? 0xffffu : 0u) | (((unsigned)(d + 5) < 16u) ? 0xffff0000u : 0u);
;                 mm.w = (((unsigned)(d + 6) < 16u) ? 0xffffu : 0u) | (((unsigned)(d + 7) < 16u) ? 0xffff0000u : 0u);
;                 mskl[bi * 64 + lane] = mm;
;             }
;     }
.LBB0_643:
	s_or_b64 exec, exec, s[38:39]
	s_waitcnt vmcnt(0)
	ds_write_b128 v2, v[8:11]
	ds_write_b128 v2, v[12:15] offset:8192
	ds_write_b128 v2, v[16:19] offset:16384
	ds_write_b128 v2, v[20:23] offset:24576
	ds_write_b128 v2, v[24:27] offset:32768
	ds_write_b128 v2, v[28:31] offset:40960
	ds_write_b128 v2, v[32:35] offset:49152
	s_movk_i32 s38, 0x100
	v_cmp_gt_i32_e32 vcc, s38, v0
	s_and_saveexec_b64 s[38:39], vcc
	ds_write_b128 v2, v[36:39] offset:57344
	s_or_b64 exec, exec, s[38:39]
	v_bfe_u32 v3, v0, 4, 2
	v_and_b32_e32 v188, 15, v0
	v_and_b32_e32 v2, 63, v0
	s_cmp_lt_u32 s40, 64
	v_lshlrev_b32_e32 v0, 3, v3
	s_waitcnt vmcnt(0) lgkmcnt(0)
	s_barrier
	s_cbranch_scc0 .LBB0_645
	v_sub_u32_e64 v4, v188, 8 clamp
	v_sub_u32_e32 v7, v0, v4
	v_cmp_gt_u32_e32 vcc, 16, v7
	v_mov_b32_e32 v12, 0xffff
	v_add_u32_e32 v5, 1, v7
	v_cndmask_b32_e32 v4, 0, v12, vcc
	v_cmp_gt_u32_e32 vcc, 16, v5
	v_mov_b32_e32 v13, 0xffff0000
	v_add_u32_e32 v6, 3, v7
	v_cndmask_b32_e32 v5, 0, v13, vcc
	v_or_b32_e32 v4, v5, v4
	v_add_u32_e32 v5, 2, v7
	v_cmp_gt_u32_e32 vcc, 16, v5
	v_add_u32_e32 v9, 5, v7
	v_lshl_add_u32 v1, v2, 4, 0
	v_cndmask_b32_e32 v5, 0, v12, vcc
	v_cmp_gt_u32_e32 vcc, 16, v6
	v_add_u32_e32 v8, 0xf800, v1
	s_movk_i32 s22, 0xffe0
	v_cndmask_b32_e32 v6, 0, v13, vcc
	v_or_b32_e32 v5, v5, v6
	v_add_u32_e32 v6, 4, v7
	v_cmp_gt_u32_e32 vcc, 16, v6
	s_nop 1
	v_cndmask_b32_e32 v6, 0, v12, vcc
	v_cmp_gt_u32_e32 vcc, 16, v9
	s_nop 1
	v_cndmask_b32_e32 v9, 0, v13, vcc
	v_or_b32_e32 v6, v6, v9
	v_add_u32_e32 v9, 6, v7
	v_cmp_gt_u32_e32 vcc, 16, v9
	v_add_u32_e32 v7, 7, v7
	s_nop 0
	v_cndmask_b32_e32 v9, 0, v12, vcc
	v_cmp_gt_u32_e32 vcc, 16, v7
	s_nop 1
	v_cndmask_b32_e32 v7, 0, v13, vcc
	v_or_b32_e32 v7, v9, v7
	v_sub_u32_e32 v9, v0, v188
	v_add_u32_e32 v10, -8, v9
	ds_write_b128 v1, v[4:7] offset:63488
	v_cmp_gt_u32_e32 vcc, 16, v10
	v_add_u32_e32 v5, -7, v9
	v_add_u32_e32 v6, -5, v9
	v_cndmask_b32_e32 v4, 0, v12, vcc
	v_cmp_gt_u32_e32 vcc, 16, v5
	v_add_u32_e32 v7, -3, v9
	v_add_u32_e32 v11, -1, v9
	v_cndmask_b32_e32 v5, 0, v13, vcc
	v_or_b32_e32 v4, v5, v4
	v_add_u32_e32 v5, -6, v9
	v_cmp_gt_u32_e32 vcc, 16, v5
	s_nop 1
	v_cndmask_b32_e32 v5, 0, v12, vcc
	v_cmp_gt_u32_e32 vcc, 16, v6
	s_nop 1
	v_cndmask_b32_e32 v6, 0, v13, vcc
	v_or_b32_e32 v5, v5, v6
	v_add_u32_e32 v6, -4, v9
	v_cmp_gt_u32_e32 vcc, 16, v6
	s_nop 1
	v_cndmask_b32_e32 v6, 0, v12, vcc
	v_cmp_gt_u32_e32 vcc, 16, v7
	s_nop 1
	v_cndmask_b32_e32 v7, 0, v13, vcc
	v_or_b32_e32 v6, v6, v7
	v_add_u32_e32 v7, -2, v9
	v_cmp_gt_u32_e32 vcc, 16, v7
	s_nop 1
	v_cndmask_b32_e32 v7, 0, v12, vcc
	v_cmp_gt_u32_e32 vcc, 16, v11
	s_nop 1
	v_cndmask_b32_e32 v11, 0, v13, vcc
	v_or_b32_e32 v7, v7, v11
	ds_write_b128 v1, v[4:7] offset:64512
	v_and_b32_e32 v1, -16, v10
	v_cmp_eq_u32_e32 vcc, s22, v1
	v_add_u32_e32 v4, 25, v9
	v_add_u32_e32 v5, 27, v9
	v_cndmask_b32_e32 v1, 0, v12, vcc
	v_cmp_gt_u32_e32 vcc, 16, v4
	v_add_u32_e32 v6, 29, v9
	v_subrev_u32_e32 v10, 17, v9
	v_cndmask_b32_e32 v4, 0, v13, vcc
	v_or_b32_e32 v4, v4, v1
	v_add_u32_e32 v1, 26, v9
	v_cmp_gt_u32_e32 vcc, 16, v1
	s_nop 1
	v_cndmask_b32_e32 v1, 0, v12, vcc
	v_cmp_gt_u32_e32 vcc, 16, v5
	s_nop 1
	v_cndmask_b32_e32 v5, 0, v13, vcc
	v_or_b32_e32 v5, v1, v5
	v_add_u32_e32 v1, 28, v9
	v_cmp_gt_u32_e32 vcc, 16, v1
	s_nop 1
	v_cndmask_b32_e32 v1, 0, v12, vcc
	v_cmp_gt_u32_e32 vcc, 16, v6
	s_nop 1
	v_cndmask_b32_e32 v6, 0, v13, vcc
	v_or_b32_e32 v6, v1, v6
	v_add_u32_e32 v1, 30, v9
	v_cmp_gt_u32_e32 vcc, 16, v1
	v_subrev_u32_e32 v1, 24, v9
	s_nop 0
	v_cndmask_b32_e32 v7, 0, v12, vcc
	ds_write_b128 v8, v[4:7] offset:2048
	v_cmp_gt_u32_e32 vcc, 16, v1
	v_subrev_u32_e32 v5, 23, v9
	v_subrev_u32_e32 v6, 21, v9
	v_cndmask_b32_e32 v4, 0, v12, vcc
	v_cmp_gt_u32_e32 vcc, 16, v5
	v_subrev_u32_e32 v7, 19, v9
	v_and_b32_e32 v1, -16, v1
	v_cndmask_b32_e32 v5, 0, v13, vcc
	v_or_b32_e32 v4, v5, v4
	v_subrev_u32_e32 v5, 22, v9
	v_cmp_gt_u32_e32 vcc, 16, v5
	s_nop 1
	v_cndmask_b32_e32 v5, 0, v12, vcc
	v_cmp_gt_u32_e32 vcc, 16, v6
	s_nop 1
	v_cndmask_b32_e32 v6, 0, v13, vcc
	v_or_b32_e32 v5, v5, v6
	v_subrev_u32_e32 v6, 20, v9
	v_cmp_gt_u32_e32 vcc, 16, v6
	s_nop 1
	v_cndmask_b32_e32 v6, 0, v12, vcc
	v_cmp_gt_u32_e32 vcc, 16, v7
	s_nop 1
	v_cndmask_b32_e32 v7, 0, v13, vcc
	v_or_b32_e32 v6, v6, v7
	v_subrev_u32_e32 v7, 18, v9
	v_cmp_gt_u32_e32 vcc, 16, v7
	s_nop 1
	v_cndmask_b32_e32 v7, 0, v12, vcc
	v_cmp_gt_u32_e32 vcc, 16, v10
	s_nop 1
	v_cndmask_b32_e32 v10, 0, v13, vcc
	v_or_b32_e32 v7, v7, v10
	ds_write_b128 v8, v[4:7] offset:3072
	v_cmp_eq_u32_e32 vcc, s22, v1
	v_add_u32_e32 v4, 9, v9
	v_add_u32_e32 v5, 11, v9
	v_cndmask_b32_e32 v1, 0, v12, vcc
	v_cmp_gt_u32_e32 vcc, 16, v4
	v_add_u32_e32 v6, 13, v9
	v_add_u32_e32 v7, 15, v9
	v_cndmask_b32_e32 v4, 0, v13, vcc
	v_or_b32_e32 v4, v4, v1
	v_add_u32_e32 v1, 10, v9
	v_cmp_gt_u32_e32 vcc, 16, v1
	s_nop 1
	v_cndmask_b32_e32 v1, 0, v12, vcc
	v_cmp_gt_u32_e32 vcc, 16, v5
	s_nop 1
	v_cndmask_b32_e32 v5, 0, v13, vcc
	v_or_b32_e32 v5, v1, v5
	v_add_u32_e32 v1, 12, v9
	v_cmp_gt_u32_e32 vcc, 16, v1
	s_nop 1
	v_cndmask_b32_e32 v1, 0, v12, vcc
	v_cmp_gt_u32_e32 vcc, 16, v6
	s_nop 1
	v_cndmask_b32_e32 v6, 0, v13, vcc
	v_or_b32_e32 v6, v1, v6
	v_add_u32_e32 v1, 14, v9
	v_cmp_gt_u32_e32 vcc, 16, v1
	s_nop 1
	v_cndmask_b32_e32 v1, 0, v12, vcc
	v_cmp_gt_u32_e32 vcc, 16, v7
	s_nop 1
	v_cndmask_b32_e32 v7, 0, v13, vcc
	v_or_b32_e32 v7, v1, v7
	v_min_u32_e32 v1, 8, v188
	v_sub_u32_e32 v1, v0, v1
	ds_write_b128 v8, v[4:7] offset:4096
	v_subrev_u32_e32 v4, 40, v1
	v_and_b32_e32 v4, -16, v4
	v_cmp_eq_u32_e32 vcc, s22, v4
	v_add_u32_e32 v5, -7, v1
	v_add_u32_e32 v6, -5, v1
	v_cndmask_b32_e32 v4, 0, v12, vcc
	v_cmp_gt_u32_e32 vcc, 16, v5
	v_add_u32_e32 v7, -3, v1
	s_nop 0
	v_cndmask_b32_e32 v5, 0, v13, vcc
	v_or_b32_e32 v4, v5, v4
	v_add_u32_e32 v5, -6, v1
	v_cmp_gt_u32_e32 vcc, 16, v5
	s_nop 1
	v_cndmask_b32_e32 v5, 0, v12, vcc
	v_cmp_gt_u32_e32 vcc, 16, v6
	s_nop 1
	v_cndmask_b32_e32 v6, 0, v13, vcc
	v_or_b32_e32 v5, v5, v6
	v_add_u32_e32 v6, -4, v1
	v_cmp_gt_u32_e32 vcc, 16, v6
	s_nop 1
	v_cndmask_b32_e32 v6, 0, v12, vcc
	v_cmp_gt_u32_e32 vcc, 16, v7
	s_nop 1
	v_cndmask_b32_e32 v7, 0, v13, vcc
	v_or_b32_e32 v6, v6, v7
	v_add_u32_e32 v7, -2, v1
	v_cmp_gt_u32_e32 vcc, 16, v7
	v_add_u32_e32 v1, -1, v1
	s_nop 0
	v_cndmask_b32_e32 v7, 0, v12, vcc
	v_cmp_gt_u32_e32 vcc, 16, v1
	s_nop 1
	v_cndmask_b32_e32 v1, 0, v13, vcc
	v_or_b32_e32 v7, v7, v1
	ds_write_b128 v8, v[4:7] offset:5120
